# barrier: L1 invalidate issued on arrival (overlapped with the arrive atomic) instead of after release
# speedup vs baseline: 1.0085x; 1.0085x over previous
; __device__ __forceinline__ void xcd_barrier(const XcdBarrier& b) {
;     asm volatile("s_waitcnt vmcnt(0)" ::: "memory");
;     __syncthreads();
;     if (threadIdx.x == 0) {
;         unsigned* bar = b.bar;
;         __builtin_amdgcn_s_waitcnt(0);
;         unsigned nloc = b.st[0], nx = b.st[1];
;         if (nloc == 0u) { xcd_barrier_complete(bar, b.x, nloc, nx); b.st[0] = nloc; b.st[1] = nx; }
; __global__ void __launch_bounds__(NTHREADS, 2) mk_fwd(Params P_arg) {
;     ...
;         if (did && ph + 1 < P_arg.ph_hi) { if (ph == 99) grid.sync(); else xcd_barrier(xbar); if (PROBE_DUP == 5) xcd_barrier(xbar); }
.LBB0_495:
	v_readlane_b32 s4, v247, 40
	s_add_i32 s50, s4, 1
	s_cmp_ge_i32 s50, s51
	s_cselect_b64 s[0:1], -1, 0
	s_cmp_lt_i32 s50, s51
	s_cselect_b64 s[2:3], -1, 0
	s_and_b64 s[2:3], s[16:17], s[2:3]
	s_andn2_b64 vcc, exec, s[2:3]
	s_cbranch_vccnz .LBB0_10
	s_cmpk_lg_i32 s4, 0x63
	s_mov_b64 s[4:5], -1
	s_cbranch_scc0 .LBB0_550
	s_waitcnt vmcnt(0)
	s_waitcnt vmcnt(0) lgkmcnt(0)
	s_barrier
	s_mov_b64 s[4:5], exec
	v_readlane_b32 s2, v248, 4
	v_readlane_b32 s3, v248, 5
	s_and_b64 s[2:3], s[4:5], s[2:3]
	s_mov_b64 exec, s[2:3]
	s_cbranch_execz .LBB0_549
	v_readlane_b32 s2, v247, 27
	s_waitcnt vmcnt(0) expcnt(0) lgkmcnt(0)
	buffer_inv sc1
	s_nop 0
	v_mov_b32_e32 v0, s2
	ds_read_b32 v3, v0
	v_readlane_b32 s2, v247, 28
	s_waitcnt lgkmcnt(0)
	v_cmp_ne_u32_e32 vcc, 0, v3
	v_mov_b32_e32 v0, s2
	ds_read_b32 v2, v0
	s_cbranch_vccnz .LBB0_513
	s_mov_b32 s2, 1
	s_branch .LBB0_501

; __device__ __forceinline__ unsigned xb_ld(unsigned* p)              { return __hip_atomic_load(p, __ATOMIC_RELAXED, __HIP_MEMORY_SCOPE_AGENT); }
; #define XB_SPIN(cond, bar) do { unsigned _sp = 0; while (cond) {   \
;     if ((++_sp & 255u) == 0u) { if (xb_ld(&(bar)[XB_TMO])) break; if (_sp > XB_SPIN_CAP) { atomicAdd(&(bar)[XB_TMO], 1u); break; } } } } while (0)
; __device__ __forceinline__ void xcd_barrier(const XcdBarrier& b) {
;     ...
;             XB_SPIN(xb_ld(&bar[XB_XGEN(b.x)]) == gen, bar);
;             __builtin_amdgcn_fence(__ATOMIC_ACQUIRE, "agent");
;             asm volatile("s_waitcnt vmcnt(0)" ::: "memory");
.LBB0_528:
	s_or_b64 exec, exec, s[8:9]
	s_waitcnt vmcnt(0)
	s_nop 0
	s_waitcnt vmcnt(0)

; __device__ __forceinline__ unsigned xb_ld(unsigned* p)              { return __hip_atomic_load(p, __ATOMIC_RELAXED, __HIP_MEMORY_SCOPE_AGENT); }
; __device__ __forceinline__ unsigned xb_add(unsigned* p, unsigned v) { return __hip_atomic_fetch_add(p, v, __ATOMIC_RELAXED, __HIP_MEMORY_SCOPE_AGENT); }
; #define XB_SPIN(cond, bar) do { unsigned _sp = 0; while (cond) {   \
;     if ((++_sp & 255u) == 0u) { if (xb_ld(&(bar)[XB_TMO])) break; if (_sp > XB_SPIN_CAP) { atomicAdd(&(bar)[XB_TMO], 1u); break; } } } } while (0)
; __device__ __forceinline__ void xcd_barrier(const XcdBarrier& b) {
;     ...
;             if (og + 1u == (tg + 1u) * nx) xb_add(&bar[XB_TOPGEN], 1u);
;             else XB_SPIN(xb_ld(&bar[XB_TOPGEN]) == tg, bar);
;             __builtin_amdgcn_fence(__ATOMIC_ACQUIRE, "agent");
;             xb_add(&bar[XB_XGEN(b.x)], 1u);
;             asm volatile("s_waitcnt vmcnt(0)" ::: "memory");
.LBB0_546:
	s_or_b64 exec, exec, s[6:7]
	s_mov_b64 s[6:7], exec
	v_mbcnt_lo_u32_b32 v0, s6, 0
	v_mbcnt_hi_u32_b32 v0, s7, v0
	v_cmp_eq_u32_e32 vcc, 0, v0
	s_waitcnt vmcnt(0)
	s_nop 0
	s_and_saveexec_b64 s[8:9], vcc
	s_cbranch_execz .LBB0_548
	s_bcnt1_i32_b64 s2, s[6:7]
	v_mov_b32_e32 v0, s2
	v_readlane_b32 s2, v247, 14
	v_readlane_b32 s3, v247, 15
	s_nop 4
	global_atomic_add v1, v0, s[2:3]
